# attention steady loop: row-sum chain of 32 v_add -> 15 v_pk_add + 1 add, dropped 4 canonicalizing v_max per step; + no entry grid.sync
# speedup vs baseline: 1.0063x; 1.0063x over previous
.LBB0_217:
	v_add_u32_e32 v170, s41, v240
	ds_read_b64_tr_b16 v[166:167], v170 offset:24576
	ds_read_b64_tr_b16 v[168:169], v170 offset:25088
	s_waitcnt lgkmcnt(9)
	v_mfma_f32_32x32x16_bf16 v[32:47], v[158:161], v[110:113], v[32:47]
	v_cvt_pk_bf16_f32 v126, v80, v81
	v_cvt_pk_bf16_f32 v127, v82, v83
	v_pk_add_f32 v[80:81], v[80:81], v[82:83]
	v_pk_add_f32 v[80:81], v[80:81], v[84:85]
	ds_read_b64_tr_b16 v[162:163], v170 offset:28672
	ds_read_b64_tr_b16 v[164:165], v170 offset:29184
	s_waitcnt lgkmcnt(10)
	v_mfma_f32_32x32x16_bf16 v[48:63], v[150:153], v[110:113], v[48:63]
	v_pk_add_f32 v[80:81], v[80:81], v[86:87]
	v_pk_add_f32 v[80:81], v[80:81], v[88:89]
	v_cvt_pk_bf16_f32 v128, v84, v85
	v_cvt_pk_bf16_f32 v129, v86, v87
	ds_read_b64_tr_b16 v[158:159], v170 offset:25600
	ds_read_b64_tr_b16 v[160:161], v170 offset:26112
	s_waitcnt lgkmcnt(11)
	v_mfma_f32_32x32x16_bf16 v[32:47], v[154:157], v[106:109], v[32:47]
	v_pk_add_f32 v[80:81], v[80:81], v[90:91]
	v_pk_add_f32 v[80:81], v[80:81], v[92:93]
	v_cvt_pk_bf16_f32 v122, v88, v89
	v_cvt_pk_bf16_f32 v123, v90, v91
	ds_read_b64_tr_b16 v[154:155], v170 offset:29696
	ds_read_b64_tr_b16 v[156:157], v170 offset:30208
	s_waitcnt lgkmcnt(12)
	v_mfma_f32_32x32x16_bf16 v[48:63], v[142:145], v[106:109], v[48:63]
	v_pk_add_f32 v[80:81], v[80:81], v[94:95]
	v_pk_add_f32 v[80:81], v[80:81], v[64:65]
	v_cvt_pk_bf16_f32 v124, v92, v93
	v_cvt_pk_bf16_f32 v125, v94, v95
	ds_read_b64_tr_b16 v[150:151], v170 offset:26624
	ds_read_b64_tr_b16 v[152:153], v170 offset:27136
	s_waitcnt lgkmcnt(13)
	v_mfma_f32_32x32x16_bf16 v[32:47], v[146:149], v[102:105], v[32:47]
	v_pk_add_f32 v[80:81], v[80:81], v[66:67]
	v_pk_add_f32 v[80:81], v[80:81], v[68:69]
	v_cvt_pk_bf16_f32 v118, v64, v65
	v_cvt_pk_bf16_f32 v119, v66, v67
	ds_read_b64_tr_b16 v[146:147], v170 offset:30720
	ds_read_b64_tr_b16 v[148:149], v170 offset:31232
	s_waitcnt lgkmcnt(14)
	v_mfma_f32_32x32x16_bf16 v[48:63], v[134:137], v[102:105], v[48:63]
	v_pk_add_f32 v[80:81], v[80:81], v[70:71]
	v_pk_add_f32 v[80:81], v[80:81], v[72:73]
	v_cvt_pk_bf16_f32 v120, v68, v69
	v_cvt_pk_bf16_f32 v121, v70, v71
	ds_read_b64_tr_b16 v[142:143], v170 offset:27648
	ds_read_b64_tr_b16 v[144:145], v170 offset:28160
	s_waitcnt lgkmcnt(14)
	v_mfma_f32_32x32x16_bf16 v[32:47], v[138:141], v[98:101], v[32:47]
	v_pk_add_f32 v[80:81], v[80:81], v[74:75]
	v_pk_add_f32 v[80:81], v[80:81], v[76:77]
	v_cvt_pk_bf16_f32 v114, v72, v73
	v_cvt_pk_bf16_f32 v115, v74, v75
	ds_read_b64_tr_b16 v[134:135], v170 offset:31744
	ds_read_b64_tr_b16 v[136:137], v170 offset:32256
	v_mfma_f32_32x32x16_bf16 v[48:63], v[130:133], v[98:101], v[48:63]
	v_pk_add_f32 v[80:81], v[80:81], v[78:79]
	v_add_f32_e32 v66, v80, v81
	v_cvt_pk_bf16_f32 v116, v76, v77
	v_cvt_pk_bf16_f32 v117, v78, v79
	v_lshl_add_u64 v[64:65], v[184:185], 0, s[84:85]
	s_add_i32 s6, s36, s0
	s_mov_b32 s21, m0
	s_mov_b32 m0, s6
	s_nop 0
	global_load_lds_dwordx4 v[64:65], off
	s_mov_b32 m0, s21
	v_lshl_add_u64 v[64:65], v[182:183], 0, s[84:85]
	s_add_i32 s6, s31, s16
	s_mov_b32 s21, m0
	s_mov_b32 m0, s6
	s_nop 0
	global_load_lds_dwordx4 v[64:65], off
	s_mov_b32 m0, s21
	v_max_f32_e32 v64, v32, v33
	v_max3_f32 v65, v34, v35, v49
	v_max3_f32 v64, v64, v48, v50
	v_max3_f32 v64, v64, v51, v36
	v_max3_f32 v65, v65, v38, v39
	v_max3_f32 v64, v64, v37, v52
	v_max3_f32 v65, v65, v54, v55
	v_max3_f32 v64, v64, v53, v40
	v_max3_f32 v65, v65, v42, v43
	v_max3_f32 v64, v64, v41, v56
	v_max3_f32 v65, v65, v58, v59
	v_max3_f32 v64, v64, v57, v44
	v_max3_f32 v65, v65, v46, v47
	v_max3_f32 v64, v64, v45, v60
	v_max3_f32 v65, v65, v62, v63
	v_max3_f32 v64, v64, v61, v65
	v_mov_b32_e32 v65, v64
	s_nop 1
	v_permlane32_swap_b32_e32 v64, v65
	v_max_f32_e32 v64, v64, v65
	v_cmp_lt_f32_e32 vcc, s95, v64
	s_cmp_lg_u64 vcc, 0
	v_add_f32_e32 v187, v241, v66
	s_cselect_b64 s[52:53], -1, 0
	s_cbranch_vccnz .LBB0_225

.LBB0_220:
	s_add_i32 s6, s31, 0x2000
	s_cmpk_lg_i32 s31, 0x4000
	s_cselect_b32 s6, s6, 0
	v_add_u32_e32 v188, s36, v240
	ds_read_b64_tr_b16 v[178:179], v188 offset:24576
	ds_read_b64_tr_b16 v[180:181], v188 offset:25088
	v_mfma_f32_32x32x16_bf16 v[80:95], v[170:173], v[110:113], v[80:95]
	v_cvt_pk_bf16_f32 v126, v32, v33
	v_cvt_pk_bf16_f32 v127, v34, v35
	v_pk_add_f32 v[32:33], v[32:33], v[34:35]
	v_pk_add_f32 v[32:33], v[32:33], v[36:37]
	ds_read_b64_tr_b16 v[146:147], v188 offset:28672
	ds_read_b64_tr_b16 v[148:149], v188 offset:29184
	v_mfma_f32_32x32x16_bf16 v[64:79], v[162:165], v[110:113], v[64:79]
	v_pk_add_f32 v[32:33], v[32:33], v[38:39]
	v_pk_add_f32 v[32:33], v[32:33], v[40:41]
	v_cvt_pk_bf16_f32 v128, v36, v37
	v_cvt_pk_bf16_f32 v129, v38, v39
	ds_read_b64_tr_b16 v[142:143], v188 offset:25600
	ds_read_b64_tr_b16 v[144:145], v188 offset:26112
	v_mfma_f32_32x32x16_bf16 v[80:95], v[166:169], v[106:109], v[80:95]
	v_pk_add_f32 v[32:33], v[32:33], v[42:43]
	v_pk_add_f32 v[32:33], v[32:33], v[44:45]
	v_cvt_pk_bf16_f32 v122, v40, v41
	v_cvt_pk_bf16_f32 v123, v42, v43
	ds_read_b64_tr_b16 v[134:135], v188 offset:29696
	ds_read_b64_tr_b16 v[136:137], v188 offset:30208
	v_mfma_f32_32x32x16_bf16 v[64:79], v[158:161], v[106:109], v[64:79]
	v_pk_add_f32 v[32:33], v[32:33], v[46:47]
	v_pk_add_f32 v[32:33], v[32:33], v[48:49]
	v_cvt_pk_bf16_f32 v124, v44, v45
	v_cvt_pk_bf16_f32 v125, v46, v47
	ds_read_b64_tr_b16 v[174:175], v188 offset:26624
	ds_read_b64_tr_b16 v[176:177], v188 offset:27136
	v_mfma_f32_32x32x16_bf16 v[80:95], v[154:157], v[102:105], v[80:95]
	v_pk_add_f32 v[32:33], v[32:33], v[50:51]
	v_pk_add_f32 v[32:33], v[32:33], v[52:53]
	v_cvt_pk_bf16_f32 v118, v48, v49
	v_cvt_pk_bf16_f32 v119, v50, v51
	ds_read_b64_tr_b16 v[170:171], v188 offset:30720
	ds_read_b64_tr_b16 v[172:173], v188 offset:31232
	v_mfma_f32_32x32x16_bf16 v[64:79], v[138:141], v[102:105], v[64:79]
	v_pk_add_f32 v[32:33], v[32:33], v[54:55]
	v_pk_add_f32 v[32:33], v[32:33], v[56:57]
	v_cvt_pk_bf16_f32 v120, v52, v53
	v_cvt_pk_bf16_f32 v121, v54, v55
	ds_read_b64_tr_b16 v[166:167], v188 offset:27648
	ds_read_b64_tr_b16 v[168:169], v188 offset:28160
	v_mfma_f32_32x32x16_bf16 v[80:95], v[150:153], v[98:101], v[80:95]
	v_pk_add_f32 v[32:33], v[32:33], v[58:59]
	v_pk_add_f32 v[32:33], v[32:33], v[60:61]
	v_cvt_pk_bf16_f32 v114, v56, v57
	v_cvt_pk_bf16_f32 v115, v58, v59
	ds_read_b64_tr_b16 v[162:163], v188 offset:31744
	ds_read_b64_tr_b16 v[164:165], v188 offset:32256
	v_mfma_f32_32x32x16_bf16 v[64:79], v[130:133], v[98:101], v[64:79]
	v_pk_add_f32 v[32:33], v[32:33], v[62:63]
	v_add_f32_e32 v32, v32, v33
	v_cvt_pk_bf16_f32 v116, v60, v61
	v_cvt_pk_bf16_f32 v117, v62, v63
	s_nop 3
	v_max_f32_e32 v33, v80, v81
	s_nop 2
	v_max3_f32 v34, v82, v83, v65
	v_max3_f32 v33, v33, v64, v66
	v_max3_f32 v33, v33, v67, v84
	v_max3_f32 v34, v34, v86, v87
	v_max3_f32 v33, v33, v85, v68
	v_max3_f32 v34, v34, v70, v71
	v_max3_f32 v33, v33, v69, v88
	v_max3_f32 v34, v34, v90, v91
	v_max3_f32 v33, v33, v89, v72
	v_max3_f32 v34, v34, v74, v75
	v_max3_f32 v33, v33, v73, v92
	v_max3_f32 v34, v34, v94, v95
	v_max3_f32 v33, v33, v93, v76
	v_max3_f32 v34, v34, v78, v79
	v_add_f32_e32 v241, v187, v32
	v_max3_f32 v32, v33, v77, v34
	v_mov_b32_e32 v33, v32
	s_nop 1
	v_permlane32_swap_b32_e32 v32, v33
	s_add_i32 s21, s31, s0
	s_mov_b32 s36, m0
	s_mov_b32 m0, s21
	s_nop 0
	global_load_lds_dwordx4 v[184:185], off
	s_mov_b32 m0, s36
	v_max_f32_e32 v32, v32, v33
	s_add_i32 s21, s6, s16
	s_mov_b32 s36, m0
	s_mov_b32 m0, s21
	s_nop 0
	global_load_lds_dwordx4 v[182:183], off
	s_mov_b32 m0, s36
	v_cmp_lt_f32_e32 vcc, s95, v32
	s_cmp_lg_u64 vcc, 0
	s_cselect_b64 s[52:53], -1, 0
	s_cbranch_vccnz .LBB0_228
